# attention MODE0 steady loop: LDS-DMA issues moved from phase A/B boundary into late PV gaps (V after PV mfma 6, K after 7)
# baseline (speedup 1.0000x reference)
.LBB0_798:
	v_bfe_i32 v196, v132, s101, 1
	v_add_u32_e32 v197, s10, v219
	ds_read_b64_tr_b16 v[184:185], v197 offset:24576
	ds_read_b64_tr_b16 v[186:187], v197 offset:25088
	v_mfma_f32_32x32x16_bf16 v[100:115], v[180:183], v[116:119], v[36:51]
	v_add_f32_e32 v84, v68, v69
	v_add_f32_e32 v84, v70, v84
	v_add_f32_e32 v84, v71, v84
	v_cvt_pk_bf16_f32 v68, v68, v69
	v_add_f32_e32 v84, v72, v84
	v_and_b32_e32 v148, v68, v196
	v_cvt_pk_bf16_f32 v68, v70, v71
	v_add_f32_e32 v84, v73, v84
	v_and_b32_e32 v149, v68, v196
	ds_read_b64_tr_b16 v[180:181], v197 offset:28672
	ds_read_b64_tr_b16 v[182:183], v197 offset:29184
	v_add_f32_e32 v68, v74, v84
	v_mfma_f32_32x32x16_bf16 v[84:99], v[176:179], v[116:119], v[36:51]
	v_add_f32_e32 v68, v75, v68
	v_add_f32_e32 v68, v76, v68
	v_add_f32_e32 v136, v77, v68
	v_cvt_pk_bf16_f32 v68, v72, v73
	v_and_b32_e32 v150, v68, v196
	v_cvt_pk_bf16_f32 v68, v74, v75
	v_and_b32_e32 v151, v68, v196
	ds_read_b64_tr_b16 v[68:69], v197 offset:25600
	ds_read_b64_tr_b16 v[70:71], v197 offset:26112
	v_mfma_f32_32x32x16_bf16 v[100:115], v[172:175], v[120:123], v[100:115]
	v_add_f32_e32 v72, v78, v136
	v_add_f32_e32 v72, v79, v72
	v_add_f32_e32 v72, v80, v72
	v_add_f32_e32 v136, v81, v72
	v_cvt_pk_bf16_f32 v72, v76, v77
	v_and_b32_e32 v144, v72, v196
	v_cvt_pk_bf16_f32 v72, v78, v79
	v_and_b32_e32 v145, v72, v196
	ds_read_b64_tr_b16 v[72:73], v197 offset:29696
	ds_read_b64_tr_b16 v[74:75], v197 offset:30208
	v_mfma_f32_32x32x16_bf16 v[84:99], v[168:171], v[120:123], v[84:99]
	v_add_f32_e32 v76, v82, v136
	v_add_f32_e32 v76, v83, v76
	v_add_f32_e32 v76, v52, v76
	v_add_f32_e32 v136, v53, v76
	v_cvt_pk_bf16_f32 v76, v80, v81
	v_and_b32_e32 v146, v76, v196
	v_cvt_pk_bf16_f32 v76, v82, v83
	v_and_b32_e32 v147, v76, v196
	ds_read_b64_tr_b16 v[76:77], v197 offset:26624
	ds_read_b64_tr_b16 v[78:79], v197 offset:27136
	v_mfma_f32_32x32x16_bf16 v[100:115], v[164:167], v[124:127], v[100:115]
	v_add_f32_e32 v80, v54, v136
	v_add_f32_e32 v80, v55, v80
	v_cvt_pk_bf16_f32 v52, v52, v53
	v_add_f32_e32 v80, v56, v80
	v_and_b32_e32 v140, v52, v196
	v_cvt_pk_bf16_f32 v52, v54, v55
	v_add_f32_e32 v80, v57, v80
	v_and_b32_e32 v141, v52, v196
	ds_read_b64_tr_b16 v[52:53], v197 offset:30720
	ds_read_b64_tr_b16 v[54:55], v197 offset:31232
	v_mfma_f32_32x32x16_bf16 v[84:99], v[160:163], v[124:127], v[84:99]
	v_add_f32_e32 v80, v58, v80
	v_add_f32_e32 v80, v59, v80
	v_cvt_pk_bf16_f32 v56, v56, v57
	v_add_f32_e32 v80, v60, v80
	v_and_b32_e32 v142, v56, v196
	v_cvt_pk_bf16_f32 v56, v58, v59
	v_add_f32_e32 v80, v61, v80
	v_and_b32_e32 v143, v56, v196
	ds_read_b64_tr_b16 v[56:57], v197 offset:27648
	ds_read_b64_tr_b16 v[58:59], v197 offset:28160
	v_mfma_f32_32x32x16_bf16 v[100:115], v[156:159], v[128:131], v[100:115]
	v_add_f32_e32 v80, v62, v80
	v_add_f32_e32 v80, v63, v80
	v_cvt_pk_bf16_f32 v60, v60, v61
	v_add_f32_e32 v80, v64, v80
	v_and_b32_e32 v136, v60, v196
	v_cvt_pk_bf16_f32 v60, v62, v63
	v_add_f32_e32 v80, v65, v80
	v_and_b32_e32 v137, v60, v196
	ds_read_b64_tr_b16 v[60:61], v197 offset:31744
	ds_read_b64_tr_b16 v[62:63], v197 offset:32256
	v_mfma_f32_32x32x16_bf16 v[84:99], v[152:155], v[128:131], v[84:99]
	v_add_f32_e32 v80, v66, v80
	v_cvt_pk_bf16_f32 v64, v64, v65
	v_add_f32_e32 v80, v67, v80
	v_and_b32_e32 v138, v64, v196
	v_cvt_pk_bf16_f32 v64, v66, v67
	v_and_b32_e32 v139, v64, v196
	v_and_b32_e32 v66, v80, v196
	v_add_f32_e32 v204, v220, v66
.LBB0_799:
	s_waitcnt lgkmcnt(14)
	v_mfma_f32_32x32x16_bf16 v[20:35], v[148:151], v[184:187], v[20:35]
	v_exp_f32_e32 v100, v100
	v_exp_f32_e32 v101, v101
	v_exp_f32_e32 v102, v102
	v_exp_f32_e32 v103, v103
	s_waitcnt lgkmcnt(12)
	v_mfma_f32_32x32x16_bf16 v[4:19], v[148:151], v[180:183], v[4:19]
	v_exp_f32_e32 v104, v104
	v_exp_f32_e32 v105, v105
	v_exp_f32_e32 v106, v106
	v_exp_f32_e32 v107, v107
	v_add_u32_e32 v80, s24, v218
	ds_read_b128 v[64:67], v80
	ds_read_b128 v[180:183], v80 offset:512
	s_waitcnt lgkmcnt(12)
	v_mfma_f32_32x32x16_bf16 v[20:35], v[144:147], v[68:71], v[20:35]
	v_exp_f32_e32 v108, v108
	v_exp_f32_e32 v109, v109
	v_exp_f32_e32 v110, v110
	v_exp_f32_e32 v111, v111
	ds_read_b128 v[184:187], v80 offset:2048
	ds_read_b128 v[176:179], v80 offset:2560
	s_waitcnt lgkmcnt(12)
	v_mfma_f32_32x32x16_bf16 v[4:19], v[144:147], v[72:75], v[4:19]
	v_exp_f32_e32 v112, v112
	v_exp_f32_e32 v113, v113
	v_exp_f32_e32 v114, v114
	v_exp_f32_e32 v115, v115
	ds_read_b128 v[172:175], v80 offset:4096
	ds_read_b128 v[168:171], v80 offset:4608
	s_waitcnt lgkmcnt(12)
	v_mfma_f32_32x32x16_bf16 v[20:35], v[140:143], v[76:79], v[20:35]
	v_exp_f32_e32 v84, v84
	v_exp_f32_e32 v85, v85
	v_exp_f32_e32 v86, v86
	v_exp_f32_e32 v87, v87
	ds_read_b128 v[164:167], v80 offset:6144
	ds_read_b128 v[160:163], v80 offset:6656
	s_waitcnt lgkmcnt(12)
	v_mfma_f32_32x32x16_bf16 v[4:19], v[140:143], v[52:55], v[4:19]
	s_mov_b32 s22, 0xfffe0000
	s_mov_b32 s23, -1
	v_lshl_add_u64 v[196:197], v[192:193], 0, s[22:23]
	s_add_i32 s10, s24, s47
	s_mov_b32 m0, s10
	s_nop 0
	global_load_lds_dwordx4 v[196:197], off
	v_exp_f32_e32 v88, v88
	v_exp_f32_e32 v89, v89
	v_exp_f32_e32 v90, v90
	v_exp_f32_e32 v91, v91
	s_waitcnt lgkmcnt(10)
	v_mfma_f32_32x32x16_bf16 v[20:35], v[136:139], v[56:59], v[20:35]
	v_lshl_add_u64 v[196:197], v[194:195], 0, s[22:23]
	s_add_i32 s10, s25, s46
	s_mov_b32 m0, s10
	s_nop 0
	global_load_lds_dwordx4 v[196:197], off
	v_exp_f32_e32 v92, v92
	v_exp_f32_e32 v93, v93
	v_exp_f32_e32 v94, v94
	v_exp_f32_e32 v95, v95
	s_waitcnt lgkmcnt(8)
	v_mfma_f32_32x32x16_bf16 v[4:19], v[136:139], v[60:63], v[4:19]
	v_exp_f32_e32 v96, v96
	v_exp_f32_e32 v97, v97
	v_exp_f32_e32 v98, v98
	v_exp_f32_e32 v99, v99
	s_add_i32 s101, s101, 1
	s_add_i32 s10, s24, 0x2000
	s_cmpk_lg_i32 s24, 0x4000
	s_cselect_b32 s54, s10, 0
	s_waitcnt vmcnt(2) lgkmcnt(0)
	s_barrier

.LBB0_802:
	s_waitcnt lgkmcnt(14)
	v_mfma_f32_32x32x16_bf16 v[20:35], v[148:151], v[152:155], v[20:35]
	v_exp_f32_e32 v68, v68
	v_exp_f32_e32 v69, v69
	v_exp_f32_e32 v70, v70
	v_exp_f32_e32 v71, v71
	s_waitcnt lgkmcnt(12)
	v_mfma_f32_32x32x16_bf16 v[4:19], v[148:151], v[156:159], v[4:19]
	v_exp_f32_e32 v72, v72
	v_exp_f32_e32 v73, v73
	v_exp_f32_e32 v74, v74
	v_exp_f32_e32 v75, v75
	v_add_u32_e32 v96, s54, v218
	ds_read_b128 v[180:183], v96
	ds_read_b128 v[176:179], v96 offset:512
	s_waitcnt lgkmcnt(12)
	v_mfma_f32_32x32x16_bf16 v[20:35], v[144:147], v[100:103], v[20:35]
	v_exp_f32_e32 v76, v76
	v_exp_f32_e32 v77, v77
	v_exp_f32_e32 v78, v78
	v_exp_f32_e32 v79, v79
	ds_read_b128 v[172:175], v96 offset:2048
	ds_read_b128 v[168:171], v96 offset:2560
	s_waitcnt lgkmcnt(12)
	v_mfma_f32_32x32x16_bf16 v[4:19], v[144:147], v[104:107], v[4:19]
	v_exp_f32_e32 v80, v80
	v_exp_f32_e32 v81, v81
	v_exp_f32_e32 v82, v82
	v_exp_f32_e32 v83, v83
	ds_read_b128 v[164:167], v96 offset:4096
	ds_read_b128 v[160:163], v96 offset:4608
	s_waitcnt lgkmcnt(12)
	v_mfma_f32_32x32x16_bf16 v[20:35], v[140:143], v[108:111], v[20:35]
	v_exp_f32_e32 v52, v52
	v_exp_f32_e32 v53, v53
	v_exp_f32_e32 v54, v54
	v_exp_f32_e32 v55, v55
	ds_read_b128 v[156:159], v96 offset:6144
	ds_read_b128 v[152:155], v96 offset:6656
	s_waitcnt lgkmcnt(12)
	v_mfma_f32_32x32x16_bf16 v[4:19], v[140:143], v[84:87], v[4:19]
	s_add_i32 s10, s54, s47
	s_mov_b32 m0, s10
	s_nop 0
	global_load_lds_dwordx4 v[192:193], off
	v_exp_f32_e32 v56, v56
	v_exp_f32_e32 v57, v57
	v_exp_f32_e32 v58, v58
	v_exp_f32_e32 v59, v59
	s_waitcnt lgkmcnt(10)
	v_mfma_f32_32x32x16_bf16 v[20:35], v[136:139], v[88:91], v[20:35]
	s_add_i32 s10, s24, s46
	s_mov_b32 m0, s10
	s_nop 0
	global_load_lds_dwordx4 v[194:195], off
	v_exp_f32_e32 v60, v60
	v_exp_f32_e32 v61, v61
	v_exp_f32_e32 v62, v62
	v_exp_f32_e32 v63, v63
	s_waitcnt lgkmcnt(8)
	v_mfma_f32_32x32x16_bf16 v[4:19], v[136:139], v[92:95], v[4:19]
	v_exp_f32_e32 v64, v64
	v_exp_f32_e32 v65, v65
	v_exp_f32_e32 v66, v66
	v_exp_f32_e32 v67, v67
	s_add_i32 s101, s101, 1
	s_cmp_eq_u32 s101, 32
	s_cbranch_scc1 .Lattn0_rot
